# P6: five of sixteen output pieces per lane kept in spare VGPRs and stored one per iteration inside the next K-loop
# speedup vs baseline: 1.0017x; 1.0017x over previous
.LBB0_770:
	s_mov_b64 s[16:17], 0x80
	s_and_b32 s1, s1, 3
	s_add_i32 m0, s54, 0x18000
	v_lshl_add_u64 v[8:9], v[8:9], 0, s[16:17]
	s_lshl_b32 s59, s7, 6
	s_lshl_b32 s7, s7, 13
	s_lshl_b32 s8, s1, 12
	s_waitcnt vmcnt(2)
	s_barrier
	global_load_lds_dwordx4 v[8:9], off
	v_lshl_add_u64 v[6:7], v[6:7], 0, s[16:17]
	s_add_i32 m0, s54, 0x1a000
	s_add_i32 s60, s54, 0x8000
	s_add_i32 s61, s54, 0xa000
	global_load_lds_dwordx4 v[6:7], off
	v_lshl_add_u64 v[2:3], v[2:3], 0, s[16:17]
	s_mov_b32 m0, s60
	s_add_u32 s36, s50, 0x40080
	global_load_lds_dwordx4 v[2:3], off
	v_lshl_add_u64 v[2:3], v[4:5], 0, s[16:17]
	s_mov_b32 m0, s61
	s_addc_u32 s37, s51, 0
	global_load_lds_dwordx4 v[2:3], off
	s_add_i32 m0, s54, 0x1c000
	v_lshl_add_u64 v[2:3], s[36:37], 0, v[132:133]
	global_load_lds_dwordx4 v[2:3], off
	v_lshl_add_u64 v[2:3], s[36:37], 0, v[136:137]
	s_add_i32 m0, s54, 0x1e000
	v_bfe_u32 v150, v10, 4, 2
	global_load_lds_dwordx4 v[2:3], off
	v_and_b32_e32 v1, 15, v10
	v_lshlrev_b32_e32 v2, 4, v150
	v_lshlrev_b32_e32 v3, 2, v10
	v_lshl_or_b32 v2, v1, 6, v2
	v_and_b32_e32 v3, 32, v3
	v_bitop3_b32 v4, v2, s7, v3 bitop3:0xde
	v_bitop3_b32 v151, v2, s8, v3 bitop3:0xde
	v_lshlrev_b32_e32 v2, 14, v11
	v_and_b32_e32 v2, 0xffff8000, v2
	v_lshl_add_u32 v2, v12, 11, v2
	v_and_b32_e32 v3, 1, v11
	v_lshl_or_b32 v2, v3, 6, v2
	v_lshl_add_u32 v140, v13, 1, v2
	v_lshlrev_b32_e32 v2, 14, v14
	v_and_b32_e32 v2, 0xffff8000, v2
	s_waitcnt vmcnt(6)
	s_cmpk_lt_u32 s6, 0x100
	v_lshl_add_u32 v2, v15, 11, v2
	v_and_b32_e32 v3, 1, v14
	s_sext_i32_i8 s5, s0
	s_cselect_b64 s[36:37], -1, 0
	s_lshl_b32 s0, s1, 6
	v_lshl_or_b32 v2, v3, 6, v2
	s_add_i32 s63, 0, 0x10000
	s_add_i32 s64, 0, 0x14000
	s_ashr_i32 s62, s3, 31
	v_mov_b32_e32 v141, v139
	v_lshl_add_u32 v142, v16, 1, v2
	v_mov_b32_e32 v143, v139
	v_mov_b64_e32 v[144:145], 0x1000
	v_mov_b64_e32 v[146:147], 0xfff
	v_add_u32_e32 v152, s63, v151
	v_add_u32_e32 v153, s64, v151
	v_add_u32_e32 v154, 0, v4
	s_lshl_b32 s8, s0, 1
	s_mov_b32 s65, 0x20000
	s_mov_b32 s66, 0x30000
	s_mov_b32 s67, 0x40000
	s_mov_b32 s68, 0x50000
	s_mov_b32 s69, 0x60000
	s_mov_b32 s70, 0x70000
	s_mov_b32 s71, 0x100000
	s_mov_b32 s72, 0x110000
	s_mov_b32 s73, 0x120000
	s_mov_b32 s74, 0x130000
	s_mov_b32 s75, 0x140000
	s_mov_b32 s76, 0x150000
	s_mov_b32 s98, 0
	s_mov_b32 s99, 5
	s_mov_b32 s77, s9
	s_barrier
	s_waitcnt vmcnt(0)
	s_branch .LBB0_773

.LBB0_780:
	ds_read_b128 v[156:159], v152
	ds_read_b128 v[160:163], v152 offset:1024
	ds_read_b128 v[164:167], v152 offset:2048
	ds_read_b128 v[168:171], v152 offset:3072
	ds_read_b128 v[172:175], v153
	ds_read_b128 v[176:179], v153 offset:1024
	ds_read_b128 v[180:183], v153 offset:2048
	ds_read_b128 v[184:187], v153 offset:3072
	s_add_u32 s6, s48, 0xfffc0080
	s_addc_u32 s7, s49, -1
	s_cmp_eq_u32 s82, 12
	s_cselect_b32 s53, s43, s7
	s_cselect_b32 s52, s78, s6
	s_cselect_b32 s51, s39, s81
	s_cselect_b32 s50, s79, s80
	v_lshl_add_u64 v[148:149], s[48:49], 0, v[140:141]
	s_add_i32 m0, s54, 0xc000
	ds_read_b128 v[188:191], v154
	ds_read_b128 v[192:195], v154 offset:1024
	ds_read_b128 v[196:199], v154 offset:2048
	ds_read_b128 v[200:203], v154 offset:3072
	ds_read_b128 v[204:207], v154 offset:4096
	ds_read_b128 v[208:211], v154 offset:5120
	ds_read_b128 v[212:215], v154 offset:6144
	ds_read_b128 v[216:219], v154 offset:7168
	global_load_lds_dwordx4 v[148:149], off
	v_lshl_add_u64 v[148:149], s[48:49], 0, v[142:143]
	s_add_i32 m0, s54, 0xe000
	s_nop 0
	global_load_lds_dwordx4 v[148:149], off
	s_waitcnt vmcnt(8)
	s_waitcnt lgkmcnt(0)
	s_barrier
	s_setprio 1
	s_waitcnt lgkmcnt(0)
	v_mfma_f32_16x16x32_bf16 v[126:129], v[156:159], v[188:191], v[126:129]
	v_mfma_f32_16x16x32_bf16 v[122:125], v[164:167], v[188:191], v[122:125]
	v_mfma_f32_16x16x32_bf16 v[110:113], v[156:159], v[196:199], v[110:113]
	v_mfma_f32_16x16x32_bf16 v[106:109], v[164:167], v[196:199], v[106:109]
	v_mfma_f32_16x16x32_bf16 v[94:97], v[156:159], v[204:207], v[94:97]
	v_mfma_f32_16x16x32_bf16 v[90:93], v[164:167], v[204:207], v[90:93]
	v_mfma_f32_16x16x32_bf16 v[78:81], v[156:159], v[212:215], v[78:81]
	v_mfma_f32_16x16x32_bf16 v[74:77], v[164:167], v[212:215], v[74:77]
	v_mfma_f32_16x16x32_bf16 v[126:129], v[160:163], v[192:195], v[126:129]
	v_mfma_f32_16x16x32_bf16 v[122:125], v[168:171], v[192:195], v[122:125]
	v_mfma_f32_16x16x32_bf16 v[110:113], v[160:163], v[200:203], v[110:113]
	v_mfma_f32_16x16x32_bf16 v[106:109], v[168:171], v[200:203], v[106:109]
	v_mfma_f32_16x16x32_bf16 v[94:97], v[160:163], v[208:211], v[94:97]
	v_mfma_f32_16x16x32_bf16 v[90:93], v[168:171], v[208:211], v[90:93]
	v_mfma_f32_16x16x32_bf16 v[78:81], v[160:163], v[216:219], v[78:81]
	v_mfma_f32_16x16x32_bf16 v[74:77], v[168:171], v[216:219], v[74:77]
	s_setprio 0
	s_setprio 1
	v_mfma_f32_16x16x32_bf16 v[118:121], v[172:175], v[188:191], v[118:121]
	v_mfma_f32_16x16x32_bf16 v[114:117], v[180:183], v[188:191], v[114:117]
	v_mfma_f32_16x16x32_bf16 v[102:105], v[172:175], v[196:199], v[102:105]
	v_mfma_f32_16x16x32_bf16 v[98:101], v[180:183], v[196:199], v[98:101]
	v_mfma_f32_16x16x32_bf16 v[86:89], v[172:175], v[204:207], v[86:89]
	v_mfma_f32_16x16x32_bf16 v[82:85], v[180:183], v[204:207], v[82:85]
	v_mfma_f32_16x16x32_bf16 v[70:73], v[172:175], v[212:215], v[70:73]
	v_mfma_f32_16x16x32_bf16 v[66:69], v[180:183], v[212:215], v[66:69]
	v_mfma_f32_16x16x32_bf16 v[118:121], v[176:179], v[192:195], v[118:121]
	v_mfma_f32_16x16x32_bf16 v[114:117], v[184:187], v[192:195], v[114:117]
	v_mfma_f32_16x16x32_bf16 v[102:105], v[176:179], v[200:203], v[102:105]
	v_mfma_f32_16x16x32_bf16 v[98:101], v[184:187], v[200:203], v[98:101]
	v_mfma_f32_16x16x32_bf16 v[86:89], v[176:179], v[208:211], v[86:89]
	v_mfma_f32_16x16x32_bf16 v[82:85], v[184:187], v[208:211], v[82:85]
	v_mfma_f32_16x16x32_bf16 v[70:73], v[176:179], v[216:219], v[70:73]
	v_mfma_f32_16x16x32_bf16 v[66:69], v[184:187], v[216:219], v[66:69]
	s_setprio 0
	s_barrier
	s_add_i32 s6, s63, s31
	v_lshl_add_u64 v[148:149], s[50:51], 0, v[132:133]
	s_mov_b32 m0, s6
	ds_read_b128 v[188:191], v154 offset:16384
	ds_read_b128 v[192:195], v154 offset:17408
	ds_read_b128 v[196:199], v154 offset:18432
	ds_read_b128 v[200:203], v154 offset:19456
	ds_read_b128 v[204:207], v154 offset:20480
	ds_read_b128 v[208:211], v154 offset:21504
	ds_read_b128 v[212:215], v154 offset:22528
	ds_read_b128 v[216:219], v154 offset:23552
	global_load_lds_dwordx4 v[148:149], off
	s_add_i32 m0, s6, 0x2000
	s_add_u32 s6, s50, 0x40000
	v_lshl_add_u64 v[220:221], s[50:51], 0, v[136:137]
	s_addc_u32 s7, s51, 0
	s_add_i32 s83, s64, s31
	global_load_lds_dwordx4 v[220:221], off
	v_lshl_add_u64 v[222:223], s[6:7], 0, v[132:133]
	s_mov_b32 m0, s83
	v_lshl_add_u64 v[224:225], s[52:53], 0, v[134:135]
	global_load_lds_dwordx4 v[222:223], off
	v_lshl_add_u64 v[222:223], s[6:7], 0, v[136:137]
	s_add_i32 m0, s83, 0x2000
	s_nop 0
	global_load_lds_dwordx4 v[222:223], off
	v_lshl_add_u64 v[222:223], s[52:53], 0, v[130:131]
	s_mov_b32 m0, s54
	s_nop 0
	global_load_lds_dwordx4 v[222:223], off
	s_mov_b32 m0, s55
	s_nop 0
	global_load_lds_dwordx4 v[224:225], off
	s_waitcnt vmcnt(8)
	s_waitcnt lgkmcnt(0)
	s_barrier
	s_setprio 1
	s_waitcnt lgkmcnt(0)
	v_mfma_f32_16x16x32_bf16 v[62:65], v[156:159], v[188:191], v[62:65]
	v_mfma_f32_16x16x32_bf16 v[58:61], v[164:167], v[188:191], v[58:61]
	v_mfma_f32_16x16x32_bf16 v[46:49], v[156:159], v[196:199], v[46:49]
	v_mfma_f32_16x16x32_bf16 v[42:45], v[164:167], v[196:199], v[42:45]
	v_mfma_f32_16x16x32_bf16 v[30:33], v[156:159], v[204:207], v[30:33]
	v_mfma_f32_16x16x32_bf16 v[26:29], v[164:167], v[204:207], v[26:29]
	v_mfma_f32_16x16x32_bf16 v[14:17], v[156:159], v[212:215], v[14:17]
	v_mfma_f32_16x16x32_bf16 v[10:13], v[164:167], v[212:215], v[10:13]
	v_mfma_f32_16x16x32_bf16 v[62:65], v[160:163], v[192:195], v[62:65]
	v_mfma_f32_16x16x32_bf16 v[58:61], v[168:171], v[192:195], v[58:61]
	v_mfma_f32_16x16x32_bf16 v[46:49], v[160:163], v[200:203], v[46:49]
	v_mfma_f32_16x16x32_bf16 v[42:45], v[168:171], v[200:203], v[42:45]
	v_mfma_f32_16x16x32_bf16 v[30:33], v[160:163], v[208:211], v[30:33]
	v_mfma_f32_16x16x32_bf16 v[26:29], v[168:171], v[208:211], v[26:29]
	v_mfma_f32_16x16x32_bf16 v[14:17], v[160:163], v[216:219], v[14:17]
	v_mfma_f32_16x16x32_bf16 v[10:13], v[168:171], v[216:219], v[10:13]
	s_setprio 0
	s_setprio 1
	v_mfma_f32_16x16x32_bf16 v[54:57], v[172:175], v[188:191], v[54:57]
	v_mfma_f32_16x16x32_bf16 v[50:53], v[180:183], v[188:191], v[50:53]
	v_mfma_f32_16x16x32_bf16 v[38:41], v[172:175], v[196:199], v[38:41]
	v_mfma_f32_16x16x32_bf16 v[34:37], v[180:183], v[196:199], v[34:37]
	v_mfma_f32_16x16x32_bf16 v[22:25], v[172:175], v[204:207], v[22:25]
	v_mfma_f32_16x16x32_bf16 v[18:21], v[180:183], v[204:207], v[18:21]
	v_mfma_f32_16x16x32_bf16 v[6:9], v[172:175], v[212:215], v[6:9]
	v_mfma_f32_16x16x32_bf16 v[2:5], v[180:183], v[212:215], v[2:5]
	v_mfma_f32_16x16x32_bf16 v[54:57], v[176:179], v[192:195], v[54:57]
	v_mfma_f32_16x16x32_bf16 v[50:53], v[184:187], v[192:195], v[50:53]
	v_mfma_f32_16x16x32_bf16 v[38:41], v[176:179], v[200:203], v[38:41]
	v_mfma_f32_16x16x32_bf16 v[34:37], v[184:187], v[200:203], v[34:37]
	v_mfma_f32_16x16x32_bf16 v[22:25], v[176:179], v[208:211], v[22:25]
	v_mfma_f32_16x16x32_bf16 v[18:21], v[184:187], v[208:211], v[18:21]
	v_mfma_f32_16x16x32_bf16 v[6:9], v[176:179], v[216:219], v[6:9]
	v_mfma_f32_16x16x32_bf16 v[2:5], v[184:187], v[216:219], v[2:5]
	s_setprio 0
	s_barrier
	s_add_i32 s83, 0, 0x18000
	v_add_u32_e32 v138, s83, v151
	s_add_i32 s84, 0, 0x1c000
	ds_read_b128 v[156:159], v138
	ds_read_b128 v[160:163], v138 offset:1024
	ds_read_b128 v[164:167], v138 offset:2048
	ds_read_b128 v[168:171], v138 offset:3072
	v_add_u32_e32 v138, s84, v151
	ds_read_b128 v[172:175], v138
	ds_read_b128 v[176:179], v138 offset:1024
	ds_read_b128 v[180:183], v138 offset:2048
	ds_read_b128 v[184:187], v138 offset:3072
	s_add_u32 s6, s52, 0x40000
	s_addc_u32 s7, s53, 0
	s_mov_b32 m0, s56
	v_lshl_add_u64 v[226:227], s[6:7], 0, v[130:131]
	ds_read_b128 v[188:191], v154 offset:32768
	ds_read_b128 v[192:195], v154 offset:33792
	ds_read_b128 v[196:199], v154 offset:34816
	ds_read_b128 v[200:203], v154 offset:35840
	ds_read_b128 v[204:207], v154 offset:36864
	ds_read_b128 v[208:211], v154 offset:37888
	ds_read_b128 v[212:215], v154 offset:38912
	ds_read_b128 v[216:219], v154 offset:39936
	global_load_lds_dwordx4 v[226:227], off
	v_lshl_add_u64 v[226:227], s[6:7], 0, v[134:135]
	s_mov_b32 m0, s57
	s_nop 0
	global_load_lds_dwordx4 v[226:227], off
	s_waitcnt vmcnt(8)
	s_waitcnt lgkmcnt(0)
	s_barrier
	s_setprio 1
	s_waitcnt lgkmcnt(0)
	v_mfma_f32_16x16x32_bf16 v[126:129], v[156:159], v[188:191], v[126:129]
	v_mfma_f32_16x16x32_bf16 v[122:125], v[164:167], v[188:191], v[122:125]
	v_mfma_f32_16x16x32_bf16 v[110:113], v[156:159], v[196:199], v[110:113]
	v_mfma_f32_16x16x32_bf16 v[106:109], v[164:167], v[196:199], v[106:109]
	v_mfma_f32_16x16x32_bf16 v[94:97], v[156:159], v[204:207], v[94:97]
	v_mfma_f32_16x16x32_bf16 v[90:93], v[164:167], v[204:207], v[90:93]
	v_mfma_f32_16x16x32_bf16 v[78:81], v[156:159], v[212:215], v[78:81]
	v_mfma_f32_16x16x32_bf16 v[74:77], v[164:167], v[212:215], v[74:77]
	v_mfma_f32_16x16x32_bf16 v[126:129], v[160:163], v[192:195], v[126:129]
	v_mfma_f32_16x16x32_bf16 v[122:125], v[168:171], v[192:195], v[122:125]
	v_mfma_f32_16x16x32_bf16 v[110:113], v[160:163], v[200:203], v[110:113]
	v_mfma_f32_16x16x32_bf16 v[106:109], v[168:171], v[200:203], v[106:109]
	v_mfma_f32_16x16x32_bf16 v[94:97], v[160:163], v[208:211], v[94:97]
	v_mfma_f32_16x16x32_bf16 v[90:93], v[168:171], v[208:211], v[90:93]
	v_mfma_f32_16x16x32_bf16 v[78:81], v[160:163], v[216:219], v[78:81]
	v_mfma_f32_16x16x32_bf16 v[74:77], v[168:171], v[216:219], v[74:77]
	s_setprio 0
	s_setprio 1
	v_mfma_f32_16x16x32_bf16 v[118:121], v[172:175], v[188:191], v[118:121]
	v_mfma_f32_16x16x32_bf16 v[114:117], v[180:183], v[188:191], v[114:117]
	v_mfma_f32_16x16x32_bf16 v[102:105], v[172:175], v[196:199], v[102:105]
	v_mfma_f32_16x16x32_bf16 v[98:101], v[180:183], v[196:199], v[98:101]
	v_mfma_f32_16x16x32_bf16 v[86:89], v[172:175], v[204:207], v[86:89]
	v_mfma_f32_16x16x32_bf16 v[82:85], v[180:183], v[204:207], v[82:85]
	v_mfma_f32_16x16x32_bf16 v[70:73], v[172:175], v[212:215], v[70:73]
	v_mfma_f32_16x16x32_bf16 v[66:69], v[180:183], v[212:215], v[66:69]
	v_mfma_f32_16x16x32_bf16 v[118:121], v[176:179], v[192:195], v[118:121]
	v_mfma_f32_16x16x32_bf16 v[114:117], v[184:187], v[192:195], v[114:117]
	v_mfma_f32_16x16x32_bf16 v[102:105], v[176:179], v[200:203], v[102:105]
	v_mfma_f32_16x16x32_bf16 v[98:101], v[184:187], v[200:203], v[98:101]
	v_mfma_f32_16x16x32_bf16 v[86:89], v[176:179], v[208:211], v[86:89]
	v_mfma_f32_16x16x32_bf16 v[82:85], v[184:187], v[208:211], v[82:85]
	v_mfma_f32_16x16x32_bf16 v[70:73], v[176:179], v[216:219], v[70:73]
	v_mfma_f32_16x16x32_bf16 v[66:69], v[184:187], v[216:219], v[66:69]
	s_setprio 0
	s_barrier
	s_add_i32 s6, s83, s31
	v_lshl_add_u64 v[148:149], v[148:149], 0, s[16:17]
	s_mov_b32 m0, s6
	ds_read_b128 v[188:191], v154 offset:49152
	ds_read_b128 v[192:195], v154 offset:50176
	ds_read_b128 v[196:199], v154 offset:51200
	ds_read_b128 v[200:203], v154 offset:52224
	ds_read_b128 v[204:207], v154 offset:53248
	ds_read_b128 v[208:211], v154 offset:54272
	ds_read_b128 v[212:215], v154 offset:55296
	ds_read_b128 v[216:219], v154 offset:56320
	global_load_lds_dwordx4 v[148:149], off
	s_add_i32 m0, s6, 0x2000
	s_add_u32 s6, s50, 0x40080
	v_lshl_add_u64 v[148:149], v[220:221], 0, s[16:17]
	s_addc_u32 s7, s51, 0
	s_add_i32 s50, s84, s31
	global_load_lds_dwordx4 v[148:149], off
	v_lshl_add_u64 v[148:149], s[6:7], 0, v[132:133]
	s_mov_b32 m0, s50
	s_nop 0
	global_load_lds_dwordx4 v[148:149], off
	v_lshl_add_u64 v[148:149], s[6:7], 0, v[136:137]
	s_add_i32 m0, s50, 0x2000
	s_nop 0
	global_load_lds_dwordx4 v[148:149], off
	v_lshl_add_u64 v[148:149], v[222:223], 0, s[16:17]
	s_mov_b32 m0, s60
	s_nop 0
	global_load_lds_dwordx4 v[148:149], off
	v_lshl_add_u64 v[148:149], v[224:225], 0, s[16:17]
	s_mov_b32 m0, s61
	s_nop 0
	global_load_lds_dwordx4 v[148:149], off
	s_waitcnt vmcnt(8)
	s_waitcnt lgkmcnt(0)
	s_barrier
	s_setprio 1
	s_waitcnt lgkmcnt(0)
	v_mfma_f32_16x16x32_bf16 v[62:65], v[156:159], v[188:191], v[62:65]
	v_mfma_f32_16x16x32_bf16 v[58:61], v[164:167], v[188:191], v[58:61]
	v_mfma_f32_16x16x32_bf16 v[46:49], v[156:159], v[196:199], v[46:49]
	v_mfma_f32_16x16x32_bf16 v[42:45], v[164:167], v[196:199], v[42:45]
	v_mfma_f32_16x16x32_bf16 v[30:33], v[156:159], v[204:207], v[30:33]
	v_mfma_f32_16x16x32_bf16 v[26:29], v[164:167], v[204:207], v[26:29]
	v_mfma_f32_16x16x32_bf16 v[14:17], v[156:159], v[212:215], v[14:17]
	v_mfma_f32_16x16x32_bf16 v[10:13], v[164:167], v[212:215], v[10:13]
	v_mfma_f32_16x16x32_bf16 v[62:65], v[160:163], v[192:195], v[62:65]
	v_mfma_f32_16x16x32_bf16 v[58:61], v[168:171], v[192:195], v[58:61]
	v_mfma_f32_16x16x32_bf16 v[46:49], v[160:163], v[200:203], v[46:49]
	v_mfma_f32_16x16x32_bf16 v[42:45], v[168:171], v[200:203], v[42:45]
	v_mfma_f32_16x16x32_bf16 v[30:33], v[160:163], v[208:211], v[30:33]
	v_mfma_f32_16x16x32_bf16 v[26:29], v[168:171], v[208:211], v[26:29]
	v_mfma_f32_16x16x32_bf16 v[14:17], v[160:163], v[216:219], v[14:17]
	v_mfma_f32_16x16x32_bf16 v[10:13], v[168:171], v[216:219], v[10:13]
	s_setprio 0
	s_setprio 1
	v_mfma_f32_16x16x32_bf16 v[54:57], v[172:175], v[188:191], v[54:57]
	v_mfma_f32_16x16x32_bf16 v[50:53], v[180:183], v[188:191], v[50:53]
	v_mfma_f32_16x16x32_bf16 v[38:41], v[172:175], v[196:199], v[38:41]
	v_mfma_f32_16x16x32_bf16 v[34:37], v[180:183], v[196:199], v[34:37]
	v_mfma_f32_16x16x32_bf16 v[22:25], v[172:175], v[204:207], v[22:25]
	v_mfma_f32_16x16x32_bf16 v[18:21], v[180:183], v[204:207], v[18:21]
	v_mfma_f32_16x16x32_bf16 v[6:9], v[172:175], v[212:215], v[6:9]
	v_mfma_f32_16x16x32_bf16 v[2:5], v[180:183], v[212:215], v[2:5]
	v_mfma_f32_16x16x32_bf16 v[54:57], v[176:179], v[192:195], v[54:57]
	v_mfma_f32_16x16x32_bf16 v[50:53], v[184:187], v[192:195], v[50:53]
	v_mfma_f32_16x16x32_bf16 v[38:41], v[176:179], v[200:203], v[38:41]
	v_mfma_f32_16x16x32_bf16 v[34:37], v[184:187], v[200:203], v[34:37]
	v_mfma_f32_16x16x32_bf16 v[22:25], v[176:179], v[208:211], v[22:25]
	v_mfma_f32_16x16x32_bf16 v[18:21], v[184:187], v[208:211], v[18:21]
	v_mfma_f32_16x16x32_bf16 v[6:9], v[176:179], v[216:219], v[6:9]
	v_mfma_f32_16x16x32_bf16 v[2:5], v[184:187], v[216:219], v[2:5]
	s_setprio 0
	s_barrier
	s_cmp_gt_u32 s99, 4
	s_cbranch_scc0 .Lpk6_go
.Lpk6_back:
	s_add_i32 s82, s82, 2
	s_add_u32 s48, s48, 0x100
	s_addc_u32 s49, s49, 0
	s_add_u32 s80, s80, 0x100
	s_addc_u32 s81, s81, 0
	s_cmp_gt_u32 s82, 13
	s_cbranch_scc0 .LBB0_780

.LBB0_783:
	s_lshl_b32 s100, s4, 8
	s_add_i32 s100, s100, s59
	s_lshl_b32 s100, s100, 13
	s_lshl_b32 s101, s5, 9
	s_add_u32 s100, s100, s101
	s_add_u32 s100, s100, s8
	s_add_u32 s100, s14, s100
	s_addc_u32 s101, s15, 0
	v_and_b32_e32 v148, 7, v1
	v_lshlrev_b32_e32 v148, 13, v148
	v_lshl_add_u32 v148, v150, 4, v148
	v_and_b32_e32 v149, 8, v1
	v_lshl_add_u32 v148, v149, 3, v148
	v_mov_b32_e32 v248, v148
	v_max_f32_e32 v122, 0, v122
	v_max_f32_e32 v123, 0, v123
	v_max_f32_e32 v124, 0, v124
	v_max_f32_e32 v125, 0, v125
	v_max_f32_e32 v126, 0, v126
	v_max_f32_e32 v127, 0, v127
	v_max_f32_e32 v128, 0, v128
	v_max_f32_e32 v129, 0, v129
	v_max_f32_e32 v114, 0, v114
	v_max_f32_e32 v115, 0, v115
	v_max_f32_e32 v116, 0, v116
	v_max_f32_e32 v117, 0, v117
	v_max_f32_e32 v118, 0, v118
	v_max_f32_e32 v119, 0, v119
	v_max_f32_e32 v120, 0, v120
	v_max_f32_e32 v121, 0, v121
	v_mul_f32_e32 v122, v122, v122
	v_mul_f32_e32 v123, v123, v123
	v_mul_f32_e32 v124, v124, v124
	v_mul_f32_e32 v125, v125, v125
	v_mul_f32_e32 v126, v126, v126
	v_mul_f32_e32 v127, v127, v127
	v_mul_f32_e32 v128, v128, v128
	v_mul_f32_e32 v129, v129, v129
	v_mul_f32_e32 v114, v114, v114
	v_mul_f32_e32 v115, v115, v115
	v_mul_f32_e32 v116, v116, v116
	v_mul_f32_e32 v117, v117, v117
	v_mul_f32_e32 v118, v118, v118
	v_mul_f32_e32 v119, v119, v119
	v_mul_f32_e32 v120, v120, v120
	v_mul_f32_e32 v121, v121, v121
	v_cvt_pk_bf16_f32 v126, v126, v127
	v_cvt_pk_bf16_f32 v127, v128, v129
	v_cvt_pk_bf16_f32 v128, v122, v123
	v_cvt_pk_bf16_f32 v129, v124, v125
	v_cvt_pk_bf16_f32 v118, v118, v119
	v_cvt_pk_bf16_f32 v119, v120, v121
	v_cvt_pk_bf16_f32 v120, v114, v115
	v_cvt_pk_bf16_f32 v121, v116, v117
	v_mov_b32_e32 v122, v126
	v_mov_b32_e32 v123, v127
	v_mov_b32_e32 v124, v128
	v_mov_b32_e32 v125, v129
	v_mov_b32_dpp v126, v118 row_ror:8 row_mask:0xf bank_mask:0xc
	v_mov_b32_dpp v127, v119 row_ror:8 row_mask:0xf bank_mask:0xc
	v_mov_b32_dpp v128, v120 row_ror:8 row_mask:0xf bank_mask:0xc
	v_mov_b32_dpp v129, v121 row_ror:8 row_mask:0xf bank_mask:0xc
	v_mov_b32_dpp v118, v122 row_ror:8 row_mask:0xf bank_mask:0x3
	v_mov_b32_dpp v119, v123 row_ror:8 row_mask:0xf bank_mask:0x3
	v_mov_b32_dpp v120, v124 row_ror:8 row_mask:0xf bank_mask:0x3
	v_mov_b32_dpp v121, v125 row_ror:8 row_mask:0xf bank_mask:0x3
	global_store_dwordx4 v148, v[126:129], s[100:101] nt
	s_add_u32 s100, s100, 0x10000
	s_addc_u32 s101, s101, 0
	global_store_dwordx4 v148, v[118:121], s[100:101] nt
	v_max_f32_e32 v106, 0, v106
	v_max_f32_e32 v107, 0, v107
	v_max_f32_e32 v108, 0, v108
	v_max_f32_e32 v109, 0, v109
	v_max_f32_e32 v110, 0, v110
	v_max_f32_e32 v111, 0, v111
	v_max_f32_e32 v112, 0, v112
	v_max_f32_e32 v113, 0, v113
	v_max_f32_e32 v98, 0, v98
	v_max_f32_e32 v99, 0, v99
	v_max_f32_e32 v100, 0, v100
	v_max_f32_e32 v101, 0, v101
	v_max_f32_e32 v102, 0, v102
	v_max_f32_e32 v103, 0, v103
	v_max_f32_e32 v104, 0, v104
	v_max_f32_e32 v105, 0, v105
	v_mul_f32_e32 v106, v106, v106
	v_mul_f32_e32 v107, v107, v107
	v_mul_f32_e32 v108, v108, v108
	v_mul_f32_e32 v109, v109, v109
	v_mul_f32_e32 v110, v110, v110
	v_mul_f32_e32 v111, v111, v111
	v_mul_f32_e32 v112, v112, v112
	v_mul_f32_e32 v113, v113, v113
	v_mul_f32_e32 v98, v98, v98
	v_mul_f32_e32 v99, v99, v99
	v_mul_f32_e32 v100, v100, v100
	v_mul_f32_e32 v101, v101, v101
	v_mul_f32_e32 v102, v102, v102
	v_mul_f32_e32 v103, v103, v103
	v_mul_f32_e32 v104, v104, v104
	v_mul_f32_e32 v105, v105, v105
	v_cvt_pk_bf16_f32 v110, v110, v111
	v_cvt_pk_bf16_f32 v111, v112, v113
	v_cvt_pk_bf16_f32 v112, v106, v107
	v_cvt_pk_bf16_f32 v113, v108, v109
	v_cvt_pk_bf16_f32 v102, v102, v103
	v_cvt_pk_bf16_f32 v103, v104, v105
	v_cvt_pk_bf16_f32 v104, v98, v99
	v_cvt_pk_bf16_f32 v105, v100, v101
	v_mov_b32_e32 v106, v110
	v_mov_b32_e32 v107, v111
	v_mov_b32_e32 v108, v112
	v_mov_b32_e32 v109, v113
	v_mov_b32_dpp v110, v102 row_ror:8 row_mask:0xf bank_mask:0xc
	v_mov_b32_dpp v111, v103 row_ror:8 row_mask:0xf bank_mask:0xc
	v_mov_b32_dpp v112, v104 row_ror:8 row_mask:0xf bank_mask:0xc
	v_mov_b32_dpp v113, v105 row_ror:8 row_mask:0xf bank_mask:0xc
	v_mov_b32_dpp v102, v106 row_ror:8 row_mask:0xf bank_mask:0x3
	v_mov_b32_dpp v103, v107 row_ror:8 row_mask:0xf bank_mask:0x3
	v_mov_b32_dpp v104, v108 row_ror:8 row_mask:0xf bank_mask:0x3
	v_mov_b32_dpp v105, v109 row_ror:8 row_mask:0xf bank_mask:0x3
	s_add_u32 s100, s100, 0x10000
	s_addc_u32 s101, s101, 0
	global_store_dwordx4 v148, v[110:113], s[100:101] nt
	s_add_u32 s100, s100, 0x10000
	s_addc_u32 s101, s101, 0
	global_store_dwordx4 v148, v[102:105], s[100:101] nt
	v_max_f32_e32 v90, 0, v90
	v_max_f32_e32 v91, 0, v91
	v_max_f32_e32 v92, 0, v92
	v_max_f32_e32 v93, 0, v93
	v_max_f32_e32 v94, 0, v94
	v_max_f32_e32 v95, 0, v95
	v_max_f32_e32 v96, 0, v96
	v_max_f32_e32 v97, 0, v97
	v_max_f32_e32 v82, 0, v82
	v_max_f32_e32 v83, 0, v83
	v_max_f32_e32 v84, 0, v84
	v_max_f32_e32 v85, 0, v85
	v_max_f32_e32 v86, 0, v86
	v_max_f32_e32 v87, 0, v87
	v_max_f32_e32 v88, 0, v88
	v_max_f32_e32 v89, 0, v89
	v_mul_f32_e32 v90, v90, v90
	v_mul_f32_e32 v91, v91, v91
	v_mul_f32_e32 v92, v92, v92
	v_mul_f32_e32 v93, v93, v93
	v_mul_f32_e32 v94, v94, v94
	v_mul_f32_e32 v95, v95, v95
	v_mul_f32_e32 v96, v96, v96
	v_mul_f32_e32 v97, v97, v97
	v_mul_f32_e32 v82, v82, v82
	v_mul_f32_e32 v83, v83, v83
	v_mul_f32_e32 v84, v84, v84
	v_mul_f32_e32 v85, v85, v85
	v_mul_f32_e32 v86, v86, v86
	v_mul_f32_e32 v87, v87, v87
	v_mul_f32_e32 v88, v88, v88
	v_mul_f32_e32 v89, v89, v89
	v_cvt_pk_bf16_f32 v94, v94, v95
	v_cvt_pk_bf16_f32 v95, v96, v97
	v_cvt_pk_bf16_f32 v96, v90, v91
	v_cvt_pk_bf16_f32 v97, v92, v93
	v_cvt_pk_bf16_f32 v86, v86, v87
	v_cvt_pk_bf16_f32 v87, v88, v89
	v_cvt_pk_bf16_f32 v88, v82, v83
	v_cvt_pk_bf16_f32 v89, v84, v85
	v_mov_b32_e32 v90, v94
	v_mov_b32_e32 v91, v95
	v_mov_b32_e32 v92, v96
	v_mov_b32_e32 v93, v97
	v_mov_b32_dpp v94, v86 row_ror:8 row_mask:0xf bank_mask:0xc
	v_mov_b32_dpp v95, v87 row_ror:8 row_mask:0xf bank_mask:0xc
	v_mov_b32_dpp v96, v88 row_ror:8 row_mask:0xf bank_mask:0xc
	v_mov_b32_dpp v97, v89 row_ror:8 row_mask:0xf bank_mask:0xc
	v_mov_b32_dpp v86, v90 row_ror:8 row_mask:0xf bank_mask:0x3
	v_mov_b32_dpp v87, v91 row_ror:8 row_mask:0xf bank_mask:0x3
	v_mov_b32_dpp v88, v92 row_ror:8 row_mask:0xf bank_mask:0x3
	v_mov_b32_dpp v89, v93 row_ror:8 row_mask:0xf bank_mask:0x3
	s_add_u32 s100, s100, 0x10000
	s_addc_u32 s101, s101, 0
	global_store_dwordx4 v148, v[94:97], s[100:101] nt
	s_add_u32 s100, s100, 0x10000
	s_addc_u32 s101, s101, 0
	global_store_dwordx4 v148, v[86:89], s[100:101] nt
	v_max_f32_e32 v74, 0, v74
	v_max_f32_e32 v75, 0, v75
	v_max_f32_e32 v76, 0, v76
	v_max_f32_e32 v77, 0, v77
	v_max_f32_e32 v78, 0, v78
	v_max_f32_e32 v79, 0, v79
	v_max_f32_e32 v80, 0, v80
	v_max_f32_e32 v81, 0, v81
	v_max_f32_e32 v66, 0, v66
	v_max_f32_e32 v67, 0, v67
	v_max_f32_e32 v68, 0, v68
	v_max_f32_e32 v69, 0, v69
	v_max_f32_e32 v70, 0, v70
	v_max_f32_e32 v71, 0, v71
	v_max_f32_e32 v72, 0, v72
	v_max_f32_e32 v73, 0, v73
	v_mul_f32_e32 v74, v74, v74
	v_mul_f32_e32 v75, v75, v75
	v_mul_f32_e32 v76, v76, v76
	v_mul_f32_e32 v77, v77, v77
	v_mul_f32_e32 v78, v78, v78
	v_mul_f32_e32 v79, v79, v79
	v_mul_f32_e32 v80, v80, v80
	v_mul_f32_e32 v81, v81, v81
	v_mul_f32_e32 v66, v66, v66
	v_mul_f32_e32 v67, v67, v67
	v_mul_f32_e32 v68, v68, v68
	v_mul_f32_e32 v69, v69, v69
	v_mul_f32_e32 v70, v70, v70
	v_mul_f32_e32 v71, v71, v71
	v_mul_f32_e32 v72, v72, v72
	v_mul_f32_e32 v73, v73, v73
	v_cvt_pk_bf16_f32 v78, v78, v79
	v_cvt_pk_bf16_f32 v79, v80, v81
	v_cvt_pk_bf16_f32 v80, v74, v75
	v_cvt_pk_bf16_f32 v81, v76, v77
	v_cvt_pk_bf16_f32 v70, v70, v71
	v_cvt_pk_bf16_f32 v71, v72, v73
	v_cvt_pk_bf16_f32 v72, v66, v67
	v_cvt_pk_bf16_f32 v73, v68, v69
	v_mov_b32_e32 v74, v78
	v_mov_b32_e32 v75, v79
	v_mov_b32_e32 v76, v80
	v_mov_b32_e32 v77, v81
	v_mov_b32_dpp v78, v70 row_ror:8 row_mask:0xf bank_mask:0xc
	v_mov_b32_dpp v79, v71 row_ror:8 row_mask:0xf bank_mask:0xc
	v_mov_b32_dpp v80, v72 row_ror:8 row_mask:0xf bank_mask:0xc
	v_mov_b32_dpp v81, v73 row_ror:8 row_mask:0xf bank_mask:0xc
	v_mov_b32_dpp v70, v74 row_ror:8 row_mask:0xf bank_mask:0x3
	v_mov_b32_dpp v71, v75 row_ror:8 row_mask:0xf bank_mask:0x3
	v_mov_b32_dpp v72, v76 row_ror:8 row_mask:0xf bank_mask:0x3
	v_mov_b32_dpp v73, v77 row_ror:8 row_mask:0xf bank_mask:0x3
	s_add_u32 s100, s100, 0x10000
	s_addc_u32 s101, s101, 0
	global_store_dwordx4 v148, v[78:81], s[100:101] nt
	s_add_u32 s100, s100, 0x10000
	s_addc_u32 s101, s101, 0
	global_store_dwordx4 v148, v[70:73], s[100:101] nt
	v_max_f32_e32 v58, 0, v58
	v_max_f32_e32 v59, 0, v59
	v_max_f32_e32 v60, 0, v60
	v_max_f32_e32 v61, 0, v61
	v_max_f32_e32 v62, 0, v62
	v_max_f32_e32 v63, 0, v63
	v_max_f32_e32 v64, 0, v64
	v_max_f32_e32 v65, 0, v65
	v_max_f32_e32 v50, 0, v50
	v_max_f32_e32 v51, 0, v51
	v_max_f32_e32 v52, 0, v52
	v_max_f32_e32 v53, 0, v53
	v_max_f32_e32 v54, 0, v54
	v_max_f32_e32 v55, 0, v55
	v_max_f32_e32 v56, 0, v56
	v_max_f32_e32 v57, 0, v57
	v_mul_f32_e32 v58, v58, v58
	v_mul_f32_e32 v59, v59, v59
	v_mul_f32_e32 v60, v60, v60
	v_mul_f32_e32 v61, v61, v61
	v_mul_f32_e32 v62, v62, v62
	v_mul_f32_e32 v63, v63, v63
	v_mul_f32_e32 v64, v64, v64
	v_mul_f32_e32 v65, v65, v65
	v_mul_f32_e32 v50, v50, v50
	v_mul_f32_e32 v51, v51, v51
	v_mul_f32_e32 v52, v52, v52
	v_mul_f32_e32 v53, v53, v53
	v_mul_f32_e32 v54, v54, v54
	v_mul_f32_e32 v55, v55, v55
	v_mul_f32_e32 v56, v56, v56
	v_mul_f32_e32 v57, v57, v57
	v_cvt_pk_bf16_f32 v62, v62, v63
	v_cvt_pk_bf16_f32 v63, v64, v65
	v_cvt_pk_bf16_f32 v64, v58, v59
	v_cvt_pk_bf16_f32 v65, v60, v61
	v_cvt_pk_bf16_f32 v54, v54, v55
	v_cvt_pk_bf16_f32 v55, v56, v57
	v_cvt_pk_bf16_f32 v56, v50, v51
	v_cvt_pk_bf16_f32 v57, v52, v53
	v_mov_b32_e32 v58, v62
	v_mov_b32_e32 v59, v63
	v_mov_b32_e32 v60, v64
	v_mov_b32_e32 v61, v65
	v_mov_b32_dpp v62, v54 row_ror:8 row_mask:0xf bank_mask:0xc
	v_mov_b32_dpp v63, v55 row_ror:8 row_mask:0xf bank_mask:0xc
	v_mov_b32_dpp v64, v56 row_ror:8 row_mask:0xf bank_mask:0xc
	v_mov_b32_dpp v65, v57 row_ror:8 row_mask:0xf bank_mask:0xc
	v_mov_b32_dpp v54, v58 row_ror:8 row_mask:0xf bank_mask:0x3
	v_mov_b32_dpp v55, v59 row_ror:8 row_mask:0xf bank_mask:0x3
	v_mov_b32_dpp v56, v60 row_ror:8 row_mask:0xf bank_mask:0x3
	v_mov_b32_dpp v57, v61 row_ror:8 row_mask:0xf bank_mask:0x3
	s_add_u32 s100, s100, 0x90000
	s_addc_u32 s101, s101, 0
	global_store_dwordx4 v148, v[62:65], s[100:101] nt
	s_add_u32 s100, s100, 0x10000
	s_addc_u32 s101, s101, 0
	global_store_dwordx4 v148, v[54:57], s[100:101] nt
	v_max_f32_e32 v42, 0, v42
	v_max_f32_e32 v43, 0, v43
	v_max_f32_e32 v44, 0, v44
	v_max_f32_e32 v45, 0, v45
	v_max_f32_e32 v46, 0, v46
	v_max_f32_e32 v47, 0, v47
	v_max_f32_e32 v48, 0, v48
	v_max_f32_e32 v49, 0, v49
	v_max_f32_e32 v34, 0, v34
	v_max_f32_e32 v35, 0, v35
	v_max_f32_e32 v36, 0, v36
	v_max_f32_e32 v37, 0, v37
	v_max_f32_e32 v38, 0, v38
	v_max_f32_e32 v39, 0, v39
	v_max_f32_e32 v40, 0, v40
	v_max_f32_e32 v41, 0, v41
	v_mul_f32_e32 v42, v42, v42
	v_mul_f32_e32 v43, v43, v43
	v_mul_f32_e32 v44, v44, v44
	v_mul_f32_e32 v45, v45, v45
	v_mul_f32_e32 v46, v46, v46
	v_mul_f32_e32 v47, v47, v47
	v_mul_f32_e32 v48, v48, v48
	v_mul_f32_e32 v49, v49, v49
	v_mul_f32_e32 v34, v34, v34
	v_mul_f32_e32 v35, v35, v35
	v_mul_f32_e32 v36, v36, v36
	v_mul_f32_e32 v37, v37, v37
	v_mul_f32_e32 v38, v38, v38
	v_mul_f32_e32 v39, v39, v39
	v_mul_f32_e32 v40, v40, v40
	v_mul_f32_e32 v41, v41, v41
	v_cvt_pk_bf16_f32 v46, v46, v47
	v_cvt_pk_bf16_f32 v47, v48, v49
	v_cvt_pk_bf16_f32 v48, v42, v43
	v_cvt_pk_bf16_f32 v49, v44, v45
	v_cvt_pk_bf16_f32 v38, v38, v39
	v_cvt_pk_bf16_f32 v39, v40, v41
	v_cvt_pk_bf16_f32 v40, v34, v35
	v_cvt_pk_bf16_f32 v41, v36, v37
	v_mov_b32_e32 v42, v46
	v_mov_b32_e32 v43, v47
	v_mov_b32_e32 v44, v48
	v_mov_b32_e32 v45, v49
	v_mov_b32_dpp v46, v38 row_ror:8 row_mask:0xf bank_mask:0xc
	v_mov_b32_dpp v47, v39 row_ror:8 row_mask:0xf bank_mask:0xc
	v_mov_b32_dpp v48, v40 row_ror:8 row_mask:0xf bank_mask:0xc
	v_mov_b32_dpp v49, v41 row_ror:8 row_mask:0xf bank_mask:0xc
	v_mov_b32_dpp v38, v42 row_ror:8 row_mask:0xf bank_mask:0x3
	v_mov_b32_dpp v39, v43 row_ror:8 row_mask:0xf bank_mask:0x3
	v_mov_b32_dpp v40, v44 row_ror:8 row_mask:0xf bank_mask:0x3
	v_mov_b32_dpp v41, v45 row_ror:8 row_mask:0xf bank_mask:0x3
	s_add_u32 s100, s100, 0x10000
	s_addc_u32 s101, s101, 0
	global_store_dwordx4 v148, v[46:49], s[100:101] nt
	s_add_u32 s100, s100, 0x10000
	s_addc_u32 s101, s101, 0
	v_mov_b32_e32 v228, v38
	v_mov_b32_e32 v229, v39
	v_mov_b32_e32 v230, v40
	v_mov_b32_e32 v231, v41
	v_max_f32_e32 v26, 0, v26
	v_max_f32_e32 v27, 0, v27
	v_max_f32_e32 v28, 0, v28
	v_max_f32_e32 v29, 0, v29
	v_max_f32_e32 v30, 0, v30
	v_max_f32_e32 v31, 0, v31
	v_max_f32_e32 v32, 0, v32
	v_max_f32_e32 v33, 0, v33
	v_max_f32_e32 v18, 0, v18
	v_max_f32_e32 v19, 0, v19
	v_max_f32_e32 v20, 0, v20
	v_max_f32_e32 v21, 0, v21
	v_max_f32_e32 v22, 0, v22
	v_max_f32_e32 v23, 0, v23
	v_max_f32_e32 v24, 0, v24
	v_max_f32_e32 v25, 0, v25
	v_mul_f32_e32 v26, v26, v26
	v_mul_f32_e32 v27, v27, v27
	v_mul_f32_e32 v28, v28, v28
	v_mul_f32_e32 v29, v29, v29
	v_mul_f32_e32 v30, v30, v30
	v_mul_f32_e32 v31, v31, v31
	v_mul_f32_e32 v32, v32, v32
	v_mul_f32_e32 v33, v33, v33
	v_mul_f32_e32 v18, v18, v18
	v_mul_f32_e32 v19, v19, v19
	v_mul_f32_e32 v20, v20, v20
	v_mul_f32_e32 v21, v21, v21
	v_mul_f32_e32 v22, v22, v22
	v_mul_f32_e32 v23, v23, v23
	v_mul_f32_e32 v24, v24, v24
	v_mul_f32_e32 v25, v25, v25
	v_cvt_pk_bf16_f32 v30, v30, v31
	v_cvt_pk_bf16_f32 v31, v32, v33
	v_cvt_pk_bf16_f32 v32, v26, v27
	v_cvt_pk_bf16_f32 v33, v28, v29
	v_cvt_pk_bf16_f32 v22, v22, v23
	v_cvt_pk_bf16_f32 v23, v24, v25
	v_cvt_pk_bf16_f32 v24, v18, v19
	v_cvt_pk_bf16_f32 v25, v20, v21
	v_mov_b32_e32 v26, v30
	v_mov_b32_e32 v27, v31
	v_mov_b32_e32 v28, v32
	v_mov_b32_e32 v29, v33
	v_mov_b32_dpp v30, v22 row_ror:8 row_mask:0xf bank_mask:0xc
	v_mov_b32_dpp v31, v23 row_ror:8 row_mask:0xf bank_mask:0xc
	v_mov_b32_dpp v32, v24 row_ror:8 row_mask:0xf bank_mask:0xc
	v_mov_b32_dpp v33, v25 row_ror:8 row_mask:0xf bank_mask:0xc
	v_mov_b32_dpp v22, v26 row_ror:8 row_mask:0xf bank_mask:0x3
	v_mov_b32_dpp v23, v27 row_ror:8 row_mask:0xf bank_mask:0x3
	v_mov_b32_dpp v24, v28 row_ror:8 row_mask:0xf bank_mask:0x3
	v_mov_b32_dpp v25, v29 row_ror:8 row_mask:0xf bank_mask:0x3
	v_mov_b32_e32 v232, v30
	v_mov_b32_e32 v233, v31
	v_mov_b32_e32 v234, v32
	v_mov_b32_e32 v235, v33
	v_mov_b32_e32 v236, v22
	v_mov_b32_e32 v237, v23
	v_mov_b32_e32 v238, v24
	v_mov_b32_e32 v239, v25
	v_max_f32_e32 v10, 0, v10
	v_max_f32_e32 v11, 0, v11
	v_max_f32_e32 v12, 0, v12
	v_max_f32_e32 v13, 0, v13
	v_max_f32_e32 v14, 0, v14
	v_max_f32_e32 v15, 0, v15
	v_max_f32_e32 v16, 0, v16
	v_max_f32_e32 v17, 0, v17
	v_max_f32_e32 v2, 0, v2
	v_max_f32_e32 v3, 0, v3
	v_max_f32_e32 v4, 0, v4
	v_max_f32_e32 v5, 0, v5
	v_max_f32_e32 v6, 0, v6
	v_max_f32_e32 v7, 0, v7
	v_max_f32_e32 v8, 0, v8
	v_max_f32_e32 v9, 0, v9
	v_mul_f32_e32 v10, v10, v10
	v_mul_f32_e32 v11, v11, v11
	v_mul_f32_e32 v12, v12, v12
	v_mul_f32_e32 v13, v13, v13
	v_mul_f32_e32 v14, v14, v14
	v_mul_f32_e32 v15, v15, v15
	v_mul_f32_e32 v16, v16, v16
	v_mul_f32_e32 v17, v17, v17
	v_mul_f32_e32 v2, v2, v2
	v_mul_f32_e32 v3, v3, v3
	v_mul_f32_e32 v4, v4, v4
	v_mul_f32_e32 v5, v5, v5
	v_mul_f32_e32 v6, v6, v6
	v_mul_f32_e32 v7, v7, v7
	v_mul_f32_e32 v8, v8, v8
	v_mul_f32_e32 v9, v9, v9
	v_cvt_pk_bf16_f32 v14, v14, v15
	v_cvt_pk_bf16_f32 v15, v16, v17
	v_cvt_pk_bf16_f32 v16, v10, v11
	v_cvt_pk_bf16_f32 v17, v12, v13
	v_cvt_pk_bf16_f32 v6, v6, v7
	v_cvt_pk_bf16_f32 v7, v8, v9
	v_cvt_pk_bf16_f32 v8, v2, v3
	v_cvt_pk_bf16_f32 v9, v4, v5
	v_mov_b32_e32 v10, v14
	v_mov_b32_e32 v11, v15
	v_mov_b32_e32 v12, v16
	v_mov_b32_e32 v13, v17
	v_mov_b32_dpp v14, v6 row_ror:8 row_mask:0xf bank_mask:0xc
	v_mov_b32_dpp v15, v7 row_ror:8 row_mask:0xf bank_mask:0xc
	v_mov_b32_dpp v16, v8 row_ror:8 row_mask:0xf bank_mask:0xc
	v_mov_b32_dpp v17, v9 row_ror:8 row_mask:0xf bank_mask:0xc
	v_mov_b32_dpp v6, v10 row_ror:8 row_mask:0xf bank_mask:0x3
	v_mov_b32_dpp v7, v11 row_ror:8 row_mask:0xf bank_mask:0x3
	v_mov_b32_dpp v8, v12 row_ror:8 row_mask:0xf bank_mask:0x3
	v_mov_b32_dpp v9, v13 row_ror:8 row_mask:0xf bank_mask:0x3
	v_mov_b32_e32 v240, v14
	v_mov_b32_e32 v241, v15
	v_mov_b32_e32 v242, v16
	v_mov_b32_e32 v243, v17
	v_mov_b32_e32 v244, v6
	v_mov_b32_e32 v245, v7
	v_mov_b32_e32 v246, v8
	v_mov_b32_e32 v247, v9
	s_mov_b32 s99, 0
	s_andn2_b64 vcc, exec, s[0:1]
	s_mov_b64 s[0:1], -1
	s_mov_b32 s98, 1
	s_cbranch_vccnz .LBB0_772
	s_andn2_b64 vcc, exec, s[10:11]
	s_cbranch_vccnz .LBB0_771
	s_barrier
	s_branch .LBB0_771

.Lrwp6_a11:
	s_waitcnt vmcnt(19)

.Lpk6_go:
	s_cmp_eq_u32 s99, 0
	s_cbranch_scc1 .Lpk6_0
	s_cmp_eq_u32 s99, 1
	s_cbranch_scc1 .Lpk6_1
	s_cmp_eq_u32 s99, 2
	s_cbranch_scc1 .Lpk6_2
	s_cmp_eq_u32 s99, 3
	s_cbranch_scc1 .Lpk6_3
.Lpk6_4:
	global_store_dwordx4 v248, v[244:247], s[100:101] nt
	s_branch .Lpk6_upd
.Lpk6_3:
	global_store_dwordx4 v248, v[240:243], s[100:101] nt
	s_branch .Lpk6_upd
.Lpk6_2:
	global_store_dwordx4 v248, v[236:239], s[100:101] nt
	s_branch .Lpk6_upd
.Lpk6_1:
	global_store_dwordx4 v248, v[232:235], s[100:101] nt
	s_branch .Lpk6_upd
.Lpk6_0:
	global_store_dwordx4 v248, v[228:231], s[100:101] nt
.Lpk6_upd:
	s_add_u32 s100, s100, 0x10000
	s_addc_u32 s101, s101, 0
	s_add_i32 s99, s99, 1
	s_branch .Lpk6_back
.LBB0_786:
	global_store_dwordx4 v248, v[228:231], s[100:101] nt
	s_add_u32 s100, s100, 0x10000
	s_addc_u32 s101, s101, 0
	global_store_dwordx4 v248, v[232:235], s[100:101] nt
	s_add_u32 s100, s100, 0x10000
	s_addc_u32 s101, s101, 0
	global_store_dwordx4 v248, v[236:239], s[100:101] nt
	s_add_u32 s100, s100, 0x10000
	s_addc_u32 s101, s101, 0
	global_store_dwordx4 v248, v[240:243], s[100:101] nt
	s_add_u32 s100, s100, 0x10000
	s_addc_u32 s101, s101, 0
	global_store_dwordx4 v248, v[244:247], s[100:101] nt
	s_mov_b32 s99, 5
	s_waitcnt vmcnt(0)
	s_barrier
